# accumulator zeroing between GEMM tiles with 64-bit moves (half the VALU instructions)
# speedup vs baseline: 1.0298x; 1.0066x over previous
; template <class Epi, class Sched, bool ALIGN_EPI = false, bool SP2 = false>
; __device__ __forceinline__ void gemm_phase(PG8_LAS unsigned char* lds, const Gemm g, const Sched& S, const Epi& E, int wid0) {
;     ...
;         const bool has_next = S.next(ui + 1, nxt);
;         const char* nA = has_next ? (const char*)g.A + (size_t)nxt.pm * tstep : cA; const char* nB = has_next ? (const char*)g.Bt + (size_t)nxt.pn * tstep : cB;
;     ...
; #pragma unroll
;         for (int a = 0; a < 2; ++a)
; #pragma unroll
;             for (int b = 0; b < 2; ++b)
; #pragma unroll
;                 for (int m = 0; m < 4; ++m)
; #pragma unroll
;                     for (int n = 0; n < 2; ++n) acc[a][b][m][n] = (f32x4){0.f, 0.f, 0.f, 0.f};
.LBB0_142:
	s_ashr_i32 s77, s76, 31
	s_lshl_b64 s[10:11], s[76:77], 19
	s_add_u32 s78, s88, s10
	s_addc_u32 s79, s89, s11
	s_and_b64 s[10:11], s[38:39], exec
	s_cselect_b32 s45, s79, s87
	s_cselect_b32 s77, s78, s86
	s_ashr_i32 s75, s74, 31
	s_lshl_b64 s[10:11], s[74:75], 19
	s_add_u32 s80, s91, s10
	s_addc_u32 s81, s92, s11
	s_and_b64 s[10:11], s[38:39], exec
	s_cselect_b32 s75, s81, s85
	s_cselect_b32 s83, s80, s84
	s_add_u32 s10, s84, 0x100
	s_addc_u32 s11, s85, 0
	s_add_u32 s84, s86, 0x40080
	v_mov_b32_e32 v0, 0
	s_addc_u32 s85, s87, 0
	s_mov_b32 s64, -2
	v_mov_b32_e32 v1, v0
	v_mov_b64_e32 v[2:3], v[0:1]
	v_mov_b64_e32 v[4:5], v[0:1]
	v_mov_b64_e32 v[6:7], v[0:1]
	v_mov_b64_e32 v[16:17], v[0:1]
	v_mov_b64_e32 v[18:19], v[0:1]
	v_mov_b64_e32 v[20:21], v[0:1]
	v_mov_b64_e32 v[22:23], v[0:1]
	v_mov_b64_e32 v[32:33], v[0:1]
	v_mov_b64_e32 v[34:35], v[0:1]
	v_mov_b64_e32 v[36:37], v[0:1]
	v_mov_b64_e32 v[38:39], v[0:1]
	v_mov_b64_e32 v[48:49], v[0:1]
	v_mov_b64_e32 v[50:51], v[0:1]
	v_mov_b64_e32 v[52:53], v[0:1]
	v_mov_b64_e32 v[54:55], v[0:1]
	v_mov_b64_e32 v[8:9], v[0:1]
	v_mov_b64_e32 v[10:11], v[0:1]
	v_mov_b64_e32 v[12:13], v[0:1]
	v_mov_b64_e32 v[14:15], v[0:1]
	v_mov_b64_e32 v[24:25], v[0:1]
	v_mov_b64_e32 v[26:27], v[0:1]
	v_mov_b64_e32 v[28:29], v[0:1]
	v_mov_b64_e32 v[30:31], v[0:1]
	v_mov_b64_e32 v[40:41], v[0:1]
	v_mov_b64_e32 v[42:43], v[0:1]
	v_mov_b64_e32 v[44:45], v[0:1]
	v_mov_b64_e32 v[46:47], v[0:1]
	v_mov_b64_e32 v[56:57], v[0:1]
	v_mov_b64_e32 v[58:59], v[0:1]
	v_mov_b64_e32 v[60:61], v[0:1]
	v_mov_b64_e32 v[62:63], v[0:1]
	v_mov_b64_e32 v[64:65], v[0:1]
	v_mov_b64_e32 v[66:67], v[0:1]
	v_mov_b64_e32 v[68:69], v[0:1]
	v_mov_b64_e32 v[70:71], v[0:1]
	v_mov_b64_e32 v[80:81], v[0:1]
	v_mov_b64_e32 v[82:83], v[0:1]
	v_mov_b64_e32 v[84:85], v[0:1]
	v_mov_b64_e32 v[86:87], v[0:1]
	v_mov_b64_e32 v[96:97], v[0:1]
	v_mov_b64_e32 v[98:99], v[0:1]
	v_mov_b64_e32 v[100:101], v[0:1]
	v_mov_b64_e32 v[102:103], v[0:1]
	v_mov_b64_e32 v[112:113], v[0:1]
	v_mov_b64_e32 v[114:115], v[0:1]
	v_mov_b64_e32 v[116:117], v[0:1]
	v_mov_b64_e32 v[118:119], v[0:1]
	v_mov_b64_e32 v[72:73], v[0:1]
	v_mov_b64_e32 v[74:75], v[0:1]
	v_mov_b64_e32 v[76:77], v[0:1]
	v_mov_b64_e32 v[78:79], v[0:1]
	v_mov_b64_e32 v[88:89], v[0:1]
	v_mov_b64_e32 v[90:91], v[0:1]
	v_mov_b64_e32 v[92:93], v[0:1]
	v_mov_b64_e32 v[94:95], v[0:1]
	v_mov_b64_e32 v[104:105], v[0:1]
	v_mov_b64_e32 v[106:107], v[0:1]
	v_mov_b64_e32 v[108:109], v[0:1]
	v_mov_b64_e32 v[110:111], v[0:1]
	v_mov_b64_e32 v[120:121], v[0:1]
	v_mov_b64_e32 v[122:123], v[0:1]
	v_mov_b64_e32 v[124:125], v[0:1]
	v_mov_b64_e32 v[126:127], v[0:1]

; template <class Epi, class Sched, bool ALIGN_EPI = false, bool SP2 = false>
; __device__ __forceinline__ void gemm_phase(PG8_LAS unsigned char* lds, const Gemm g, const Sched& S, const Epi& E, int wid0) {
;     ...
;         const bool has_next = S.next(ui + 1, nxt);
;         const char* nA = has_next ? (const char*)g.A + (size_t)nxt.pm * tstep : cA; const char* nB = has_next ? (const char*)g.Bt + (size_t)nxt.pn * tstep : cB;
;     ...
; #pragma unroll
;         for (int a = 0; a < 2; ++a)
; #pragma unroll
;             for (int b = 0; b < 2; ++b)
; #pragma unroll
;                 for (int m = 0; m < 4; ++m)
; #pragma unroll
;                     for (int n = 0; n < 2; ++n) acc[a][b][m][n] = (f32x4){0.f, 0.f, 0.f, 0.f};
.LBB0_166:
	s_ashr_i32 s75, s74, 31
	s_lshl_b64 s[10:11], s[74:75], 19
	s_add_u32 s76, s4, s10
	s_addc_u32 s77, s5, s11
	s_and_b64 s[10:11], s[38:39], exec
	s_cselect_b32 s75, s77, s85
	s_cselect_b32 s94, s76, s84
	s_ashr_i32 s73, s72, 31
	s_lshl_b64 s[10:11], s[72:73], 19
	s_add_u32 s78, s88, s10
	s_addc_u32 s79, s89, s11
	s_and_b64 s[10:11], s[38:39], exec
	s_cselect_b32 s73, s79, s83
	s_cselect_b32 s95, s78, s82
	s_add_u32 s10, s82, 0x100
	s_addc_u32 s11, s83, 0
	s_add_u32 s82, s84, 0x40080
	v_mov_b32_e32 v0, 0
	s_addc_u32 s83, s85, 0
	s_mov_b32 s64, -2
	v_mov_b32_e32 v1, v0
	v_mov_b64_e32 v[2:3], v[0:1]
	v_mov_b64_e32 v[4:5], v[0:1]
	v_mov_b64_e32 v[6:7], v[0:1]
	v_mov_b64_e32 v[12:13], v[0:1]
	v_mov_b64_e32 v[14:15], v[0:1]
	v_mov_b64_e32 v[20:21], v[0:1]
	v_mov_b64_e32 v[22:23], v[0:1]
	v_mov_b64_e32 v[28:29], v[0:1]
	v_mov_b64_e32 v[30:31], v[0:1]
	v_mov_b64_e32 v[36:37], v[0:1]
	v_mov_b64_e32 v[38:39], v[0:1]
	v_mov_b64_e32 v[44:45], v[0:1]
	v_mov_b64_e32 v[46:47], v[0:1]
	v_mov_b64_e32 v[52:53], v[0:1]
	v_mov_b64_e32 v[54:55], v[0:1]
	v_mov_b64_e32 v[8:9], v[0:1]
	v_mov_b64_e32 v[10:11], v[0:1]
	v_mov_b64_e32 v[16:17], v[0:1]
	v_mov_b64_e32 v[18:19], v[0:1]
	v_mov_b64_e32 v[24:25], v[0:1]
	v_mov_b64_e32 v[26:27], v[0:1]
	v_mov_b64_e32 v[32:33], v[0:1]
	v_mov_b64_e32 v[34:35], v[0:1]
	v_mov_b64_e32 v[40:41], v[0:1]
	v_mov_b64_e32 v[42:43], v[0:1]
	v_mov_b64_e32 v[48:49], v[0:1]
	v_mov_b64_e32 v[50:51], v[0:1]
	v_mov_b64_e32 v[56:57], v[0:1]
	v_mov_b64_e32 v[58:59], v[0:1]
	v_mov_b64_e32 v[60:61], v[0:1]
	v_mov_b64_e32 v[62:63], v[0:1]
	v_mov_b64_e32 v[64:65], v[0:1]
	v_mov_b64_e32 v[66:67], v[0:1]
	v_mov_b64_e32 v[68:69], v[0:1]
	v_mov_b64_e32 v[70:71], v[0:1]
	v_mov_b64_e32 v[80:81], v[0:1]
	v_mov_b64_e32 v[82:83], v[0:1]
	v_mov_b64_e32 v[84:85], v[0:1]
	v_mov_b64_e32 v[86:87], v[0:1]
	v_mov_b64_e32 v[112:113], v[0:1]
	v_mov_b64_e32 v[114:115], v[0:1]
	v_mov_b64_e32 v[116:117], v[0:1]
	v_mov_b64_e32 v[118:119], v[0:1]
	v_mov_b64_e32 v[128:129], v[0:1]
	v_mov_b64_e32 v[130:131], v[0:1]
	v_mov_b64_e32 v[132:133], v[0:1]
	v_mov_b64_e32 v[134:135], v[0:1]
	v_mov_b64_e32 v[72:73], v[0:1]
	v_mov_b64_e32 v[74:75], v[0:1]
	v_mov_b64_e32 v[76:77], v[0:1]
	v_mov_b64_e32 v[78:79], v[0:1]
	v_mov_b64_e32 v[88:89], v[0:1]
	v_mov_b64_e32 v[90:91], v[0:1]
	v_mov_b64_e32 v[92:93], v[0:1]
	v_mov_b64_e32 v[94:95], v[0:1]
	v_mov_b64_e32 v[120:121], v[0:1]
	v_mov_b64_e32 v[122:123], v[0:1]
	v_mov_b64_e32 v[124:125], v[0:1]
	v_mov_b64_e32 v[126:127], v[0:1]
	v_mov_b64_e32 v[136:137], v[0:1]
	v_mov_b64_e32 v[138:139], v[0:1]
	v_mov_b64_e32 v[140:141], v[0:1]
	v_mov_b64_e32 v[142:143], v[0:1]

; template <class Epi, class Sched, bool ALIGN_EPI = false, bool SP2 = false>
; __device__ __forceinline__ void gemm_phase(PG8_LAS unsigned char* lds, const Gemm g, const Sched& S, const Epi& E, int wid0) {
;     ...
;         const bool has_next = S.next(ui + 1, nxt);
;         const char* nA = has_next ? (const char*)g.A + (size_t)nxt.pm * tstep : cA; const char* nB = has_next ? (const char*)g.Bt + (size_t)nxt.pn * tstep : cB;
;     ...
; #pragma unroll
;         for (int a = 0; a < 2; ++a)
; #pragma unroll
;             for (int b = 0; b < 2; ++b)
; #pragma unroll
;                 for (int m = 0; m < 4; ++m)
; #pragma unroll
;                     for (int n = 0; n < 2; ++n) acc[a][b][m][n] = (f32x4){0.f, 0.f, 0.f, 0.f};
.LBB0_376:
	s_ashr_i32 s75, s74, 31
	s_lshl_b64 s[10:11], s[74:75], 19
	s_add_u32 s86, s6, s10
	s_addc_u32 s87, s7, s11
	s_and_b64 s[10:11], s[40:41], exec
	s_cselect_b32 s22, s87, s77
	s_cselect_b32 s75, s86, s76
	s_ashr_i32 s73, s72, 31
	s_lshl_b64 s[10:11], s[72:73], 19
	s_add_u32 s78, s44, s10
	s_addc_u32 s79, s45, s11
	s_and_b64 s[10:11], s[40:41], exec
	s_cselect_b32 s73, s79, s85
	s_cselect_b32 s81, s78, s84
	s_add_u32 s10, s84, 0x100
	s_addc_u32 s11, s85, 0
	s_add_u32 s84, s76, 0x40080
	v_mov_b32_e32 v0, 0
	s_addc_u32 s85, s77, 0
	s_mov_b32 s64, -2
	v_mov_b32_e32 v1, v0
	v_mov_b64_e32 v[2:3], v[0:1]
	v_mov_b32_e32 v4, v0
	s_waitcnt lgkmcnt(0)
	v_mov_b32_e32 v5, v0
	v_mov_b64_e32 v[6:7], v[0:1]
	v_mov_b64_e32 v[16:17], v[0:1]
	v_mov_b64_e32 v[18:19], v[0:1]
	v_mov_b64_e32 v[20:21], v[0:1]
	v_mov_b64_e32 v[22:23], v[0:1]
	v_mov_b64_e32 v[32:33], v[0:1]
	v_mov_b64_e32 v[34:35], v[0:1]
	v_mov_b64_e32 v[36:37], v[0:1]
	v_mov_b64_e32 v[38:39], v[0:1]
	v_mov_b64_e32 v[48:49], v[0:1]
	v_mov_b64_e32 v[50:51], v[0:1]
	v_mov_b64_e32 v[52:53], v[0:1]
	v_mov_b64_e32 v[54:55], v[0:1]
	v_mov_b64_e32 v[8:9], v[0:1]
	v_mov_b64_e32 v[10:11], v[0:1]
	v_mov_b64_e32 v[12:13], v[0:1]
	v_mov_b64_e32 v[14:15], v[0:1]
	v_mov_b64_e32 v[24:25], v[0:1]
	v_mov_b64_e32 v[26:27], v[0:1]
	v_mov_b64_e32 v[28:29], v[0:1]
	v_mov_b64_e32 v[30:31], v[0:1]
	v_mov_b64_e32 v[40:41], v[0:1]
	v_mov_b64_e32 v[42:43], v[0:1]
	v_mov_b64_e32 v[44:45], v[0:1]
	v_mov_b64_e32 v[46:47], v[0:1]
	v_mov_b64_e32 v[56:57], v[0:1]
	v_mov_b64_e32 v[58:59], v[0:1]
	v_mov_b64_e32 v[60:61], v[0:1]
	v_mov_b64_e32 v[62:63], v[0:1]
	v_mov_b64_e32 v[64:65], v[0:1]
	v_mov_b64_e32 v[66:67], v[0:1]
	v_mov_b64_e32 v[68:69], v[0:1]
	v_mov_b64_e32 v[70:71], v[0:1]
	v_mov_b64_e32 v[80:81], v[0:1]
	v_mov_b64_e32 v[82:83], v[0:1]
	v_mov_b64_e32 v[84:85], v[0:1]
	v_mov_b64_e32 v[86:87], v[0:1]
	v_mov_b64_e32 v[96:97], v[0:1]
	v_mov_b64_e32 v[98:99], v[0:1]
	v_mov_b64_e32 v[100:101], v[0:1]
	v_mov_b64_e32 v[102:103], v[0:1]
	v_mov_b64_e32 v[112:113], v[0:1]
	v_mov_b64_e32 v[114:115], v[0:1]
	v_mov_b64_e32 v[116:117], v[0:1]
	v_mov_b64_e32 v[118:119], v[0:1]
	v_mov_b64_e32 v[72:73], v[0:1]
	v_mov_b64_e32 v[74:75], v[0:1]
	v_mov_b64_e32 v[76:77], v[0:1]
	v_mov_b64_e32 v[78:79], v[0:1]
	v_mov_b64_e32 v[88:89], v[0:1]
	v_mov_b64_e32 v[90:91], v[0:1]
	v_mov_b64_e32 v[92:93], v[0:1]
	v_mov_b64_e32 v[94:95], v[0:1]
	v_mov_b64_e32 v[104:105], v[0:1]
	v_mov_b64_e32 v[106:107], v[0:1]
	v_mov_b64_e32 v[108:109], v[0:1]
	v_mov_b64_e32 v[110:111], v[0:1]
	v_mov_b64_e32 v[120:121], v[0:1]
	v_mov_b64_e32 v[122:123], v[0:1]
	v_mov_b64_e32 v[124:125], v[0:1]
	v_mov_b64_e32 v[126:127], v[0:1]

; template <class Epi, class Sched, bool ALIGN_EPI = false, bool SP2 = false>
; __device__ __forceinline__ void gemm_phase(PG8_LAS unsigned char* lds, const Gemm g, const Sched& S, const Epi& E, int wid0) {
;     ...
;         const bool has_next = S.next(ui + 1, nxt);
;         const char* nA = has_next ? (const char*)g.A + (size_t)nxt.pm * tstep : cA; const char* nB = has_next ? (const char*)g.Bt + (size_t)nxt.pn * tstep : cB;
;     ...
; #pragma unroll
;         for (int a = 0; a < 2; ++a)
; #pragma unroll
;             for (int b = 0; b < 2; ++b)
; #pragma unroll
;                 for (int m = 0; m < 4; ++m)
; #pragma unroll
;                     for (int n = 0; n < 2; ++n) acc[a][b][m][n] = (f32x4){0.f, 0.f, 0.f, 0.f};
.LBB0_543:
	s_ashr_i32 s73, s72, 31
	s_lshl_b64 s[10:11], s[72:73], 19
	s_add_u32 s74, s5, s10
	s_addc_u32 s75, s6, s11
	s_and_b64 s[10:11], s[38:39], exec
	s_cselect_b32 s45, s75, s83
	s_cselect_b32 s73, s74, s82
	s_ashr_i32 s71, s70, 31
	s_lshl_b64 s[10:11], s[70:71], 19
	s_add_u32 s76, s7, s10
	s_addc_u32 s77, s22, s11
	s_and_b64 s[10:11], s[38:39], exec
	s_cselect_b32 s71, s77, s81
	s_cselect_b32 s79, s76, s80
	s_add_u32 s10, s80, 0x100
	s_addc_u32 s11, s81, 0
	s_add_u32 s80, s82, 0x40080
	v_mov_b32_e32 v0, 0
	s_addc_u32 s81, s83, 0
	s_mov_b32 s64, -2
	v_mov_b32_e32 v1, v0
	v_mov_b64_e32 v[2:3], v[0:1]
	v_mov_b64_e32 v[8:9], v[0:1]
	v_mov_b64_e32 v[10:11], v[0:1]
	v_mov_b64_e32 v[16:17], v[0:1]
	v_mov_b64_e32 v[18:19], v[0:1]
	v_mov_b64_e32 v[24:25], v[0:1]
	v_mov_b64_e32 v[26:27], v[0:1]
	v_mov_b64_e32 v[32:33], v[0:1]
	v_mov_b64_e32 v[34:35], v[0:1]
	v_mov_b64_e32 v[40:41], v[0:1]
	v_mov_b64_e32 v[42:43], v[0:1]
	v_mov_b64_e32 v[48:49], v[0:1]
	v_mov_b64_e32 v[50:51], v[0:1]
	v_mov_b64_e32 v[56:57], v[0:1]
	v_mov_b64_e32 v[58:59], v[0:1]
	v_mov_b64_e32 v[4:5], v[0:1]
	v_mov_b64_e32 v[6:7], v[0:1]
	v_mov_b64_e32 v[12:13], v[0:1]
	v_mov_b64_e32 v[14:15], v[0:1]
	v_mov_b64_e32 v[20:21], v[0:1]
	v_mov_b64_e32 v[22:23], v[0:1]
	v_mov_b64_e32 v[28:29], v[0:1]
	v_mov_b64_e32 v[30:31], v[0:1]
	v_mov_b64_e32 v[36:37], v[0:1]
	v_mov_b64_e32 v[38:39], v[0:1]
	v_mov_b64_e32 v[44:45], v[0:1]
	v_mov_b64_e32 v[46:47], v[0:1]
	v_mov_b64_e32 v[52:53], v[0:1]
	v_mov_b64_e32 v[54:55], v[0:1]
	v_mov_b64_e32 v[60:61], v[0:1]
	v_mov_b64_e32 v[62:63], v[0:1]
	v_mov_b64_e32 v[64:65], v[0:1]
	v_mov_b64_e32 v[66:67], v[0:1]
	v_mov_b64_e32 v[72:73], v[0:1]
	v_mov_b64_e32 v[74:75], v[0:1]
	v_mov_b64_e32 v[80:81], v[0:1]
	v_mov_b64_e32 v[82:83], v[0:1]
	v_mov_b64_e32 v[88:89], v[0:1]
	v_mov_b64_e32 v[90:91], v[0:1]
	v_mov_b64_e32 v[96:97], v[0:1]
	v_mov_b64_e32 v[98:99], v[0:1]
	v_mov_b64_e32 v[104:105], v[0:1]
	v_mov_b64_e32 v[106:107], v[0:1]
	v_mov_b64_e32 v[112:113], v[0:1]
	v_mov_b64_e32 v[114:115], v[0:1]
	v_mov_b64_e32 v[120:121], v[0:1]
	v_mov_b64_e32 v[122:123], v[0:1]
	v_mov_b64_e32 v[68:69], v[0:1]
	v_mov_b64_e32 v[70:71], v[0:1]
	v_mov_b64_e32 v[76:77], v[0:1]
	v_mov_b64_e32 v[78:79], v[0:1]
	v_mov_b64_e32 v[84:85], v[0:1]
	v_mov_b64_e32 v[86:87], v[0:1]
	v_mov_b64_e32 v[92:93], v[0:1]
	v_mov_b64_e32 v[94:95], v[0:1]
	v_mov_b64_e32 v[100:101], v[0:1]
	v_mov_b64_e32 v[102:103], v[0:1]
	v_mov_b64_e32 v[108:109], v[0:1]
	v_mov_b64_e32 v[110:111], v[0:1]
	v_mov_b64_e32 v[116:117], v[0:1]
	v_mov_b64_e32 v[118:119], v[0:1]
	v_mov_b64_e32 v[124:125], v[0:1]
	v_mov_b64_e32 v[126:127], v[0:1]

; template <class Epi, class Sched, bool ALIGN_EPI = false, bool SP2 = false>
; __device__ __forceinline__ void gemm_phase(PG8_LAS unsigned char* lds, const Gemm g, const Sched& S, const Epi& E, int wid0) {
;     ...
; #pragma unroll
;         for (int a = 0; a < 2; ++a)
; #pragma unroll
;             for (int b = 0; b < 2; ++b)
; #pragma unroll
;                 for (int m = 0; m < 4; ++m)
; #pragma unroll
;                     for (int n = 0; n < 2; ++n) acc[a][b][m][n] = (f32x4){0.f, 0.f, 0.f, 0.f};
.LBB0_629:
	s_add_u32 s10, s78, 0x100
	v_mov_b32_e32 v0, 0
	s_addc_u32 s11, s79, 0
	s_mov_b32 s64, -2
	v_mov_b32_e32 v1, v0
	v_mov_b64_e32 v[2:3], v[0:1]
	v_mov_b32_e32 v4, v0
	s_waitcnt lgkmcnt(0)
	v_mov_b32_e32 v5, v0
	v_mov_b64_e32 v[6:7], v[0:1]
	v_mov_b64_e32 v[16:17], v[0:1]
	v_mov_b64_e32 v[18:19], v[0:1]
	v_mov_b64_e32 v[20:21], v[0:1]
	v_mov_b64_e32 v[22:23], v[0:1]
	v_mov_b64_e32 v[32:33], v[0:1]
	v_mov_b64_e32 v[34:35], v[0:1]
	v_mov_b64_e32 v[36:37], v[0:1]
	v_mov_b64_e32 v[38:39], v[0:1]
	v_mov_b64_e32 v[48:49], v[0:1]
	v_mov_b64_e32 v[50:51], v[0:1]
	v_mov_b64_e32 v[52:53], v[0:1]
	v_mov_b64_e32 v[54:55], v[0:1]
	v_mov_b64_e32 v[8:9], v[0:1]
	v_mov_b64_e32 v[10:11], v[0:1]
	v_mov_b64_e32 v[12:13], v[0:1]
	v_mov_b64_e32 v[14:15], v[0:1]
	v_mov_b64_e32 v[24:25], v[0:1]
	v_mov_b64_e32 v[26:27], v[0:1]
	v_mov_b64_e32 v[28:29], v[0:1]
	v_mov_b64_e32 v[30:31], v[0:1]
	v_mov_b64_e32 v[40:41], v[0:1]
	v_mov_b64_e32 v[42:43], v[0:1]
	v_mov_b64_e32 v[44:45], v[0:1]
	v_mov_b64_e32 v[46:47], v[0:1]
	v_mov_b64_e32 v[56:57], v[0:1]
	v_mov_b64_e32 v[58:59], v[0:1]
	v_mov_b64_e32 v[60:61], v[0:1]
	v_mov_b64_e32 v[62:63], v[0:1]
	v_mov_b64_e32 v[64:65], v[0:1]
	v_mov_b64_e32 v[66:67], v[0:1]
	v_mov_b64_e32 v[68:69], v[0:1]
	v_mov_b64_e32 v[70:71], v[0:1]
	v_mov_b64_e32 v[80:81], v[0:1]
	v_mov_b64_e32 v[82:83], v[0:1]
	v_mov_b64_e32 v[84:85], v[0:1]
	v_mov_b64_e32 v[86:87], v[0:1]
	v_mov_b64_e32 v[96:97], v[0:1]
	v_mov_b64_e32 v[98:99], v[0:1]
	v_mov_b64_e32 v[100:101], v[0:1]
	v_mov_b64_e32 v[102:103], v[0:1]
	v_mov_b64_e32 v[112:113], v[0:1]
	v_mov_b64_e32 v[114:115], v[0:1]
	v_mov_b64_e32 v[116:117], v[0:1]
	v_mov_b64_e32 v[118:119], v[0:1]
	v_mov_b64_e32 v[72:73], v[0:1]
	v_mov_b64_e32 v[74:75], v[0:1]
	v_mov_b64_e32 v[76:77], v[0:1]
	v_mov_b64_e32 v[78:79], v[0:1]
	v_mov_b64_e32 v[88:89], v[0:1]
	v_mov_b64_e32 v[90:91], v[0:1]
	v_mov_b64_e32 v[92:93], v[0:1]
	v_mov_b64_e32 v[94:95], v[0:1]
	v_mov_b64_e32 v[104:105], v[0:1]
	v_mov_b64_e32 v[106:107], v[0:1]
	v_mov_b64_e32 v[108:109], v[0:1]
	v_mov_b64_e32 v[110:111], v[0:1]
	v_mov_b64_e32 v[120:121], v[0:1]
	v_mov_b64_e32 v[122:123], v[0:1]
	v_mov_b64_e32 v[124:125], v[0:1]
	v_mov_b64_e32 v[126:127], v[0:1]
